# also HGRN, attention diagonal loop, conv, prep_rows and combine loop heads aligned to 64 bytes
# baseline (speedup 1.0000x reference)
; #define LAS __attribute__((address_space(3)))
; __global__ void __launch_bounds__(512, 2) fwd_megakernel(Args a) {
;     ...
;     const int tid = threadIdx.x, lane = tid & 63, wave = __builtin_amdgcn_readfirstlane(tid >> 6);
;     const int G = gridDim.x, bx = blockIdx.x, vcu = (G % 8 == 0) ? (bx % 8) * (G / 8) + bx / 8 : bx;
;     const int gw = vcu * 8 + wave, NGW = G * 8;
;     unsigned char* ws = a.ws;
;     float* ropeC = (float*)(ws + WS_ROPE); float* ropeS = ropeC + SEQ * 8;
;     bf16* WFI = (bf16*)(ws + WS_WFI); bf16* WFO = (bf16*)(ws + WS_WFO); bf16* WIN = (bf16*)(ws + WS_WIN);
;     bf16* WPA = (bf16*)(ws + WS_WPA); bf16* WPR = (bf16*)(ws + WS_WPR); bf16* WWO = (bf16*)(ws + WS_WWO);
;     bf16* H = (bf16*)(ws + WS_H); bf16* ACT = (bf16*)(ws + WS_BIG); bf16* P = (bf16*)(ws + WS_BIG);
;     bf16* O1 = (bf16*)(ws + WS_Y); bf16* O2 = O1 + PBUF; bf16* T1 = (bf16*)(ws + WS_Y);
;     bf16* YA = P + PB_QA * PBUF; bf16* YR = P + PB_KA * PBUF;
;     float* out = a.out;
;     float* RS0 = (float*)(ws + WS_SS); float* SS1 = RS0 + M; float* SS2 = SS1 + M; float* SS3 = SS2 + M;
;     LAS float* scr = (LAS float*)(lds + wave * 16384);
;     using pg8::Gemm; using pg8::StaticOrder; using pg8::gemm_phase;
;     for (int u = tid; u < (LDS_BYTES - RING_BYTES) / 4; u += 512) ((LAS unsigned*)(lds + RING_BYTES))[u] = 0u;
;     __syncthreads();
;     ...
;     for (int i = bx * 512 + tid; i < (int)(WS_ZERO_BYTES / 4); i += G * 512) ((unsigned*)(ws + WS_BAR))[i] = 0u;
;     conv_mat<1>(a.in[I_F1I], a.in[I_F1N], DM, 2 * DFF, WFI, scr, gw, NGW, lane);
.LBB0_18:
	s_or_b64 exec, exec, s[6:7]
	s_lshr_b32 s3, s3, 6
	s_lshl_b32 s4, s66, 3
	s_lshl_b32 s5, s3, 14
	s_add_i32 s34, s4, s3
	s_add_i32 s3, s5, 0
	s_load_dwordx2 s[4:5], s[0:1], 0xb0
	s_load_dwordx16 s[16:31], s[0:1], 0x0
	v_writelane_b32 v250, s3, 3
	v_and_b32_e32 v223, 63, v222
	v_lshrrev_b32_e32 v224, 3, v223
	s_waitcnt lgkmcnt(0)
	s_lshl_b32 s64, s4, 3
	s_add_u32 s4, s62, 0x100000
	s_addc_u32 s5, s63, 0
	s_cmpk_lt_i32 s34, 0x2c00
	v_writelane_b32 v250, s4, 4
	s_cselect_b64 s[6:7], -1, 0
	s_cmpk_gt_i32 s34, 0x2bff
	v_and_b32_e32 v225, 7, v222
	v_writelane_b32 v250, s5, 5
	s_cbranch_scc1 .LBB0_33
	v_readlane_b32 s8, v250, 4
	v_lshlrev_b32_e32 v2, 4, v225
	v_mov_b32_e32 v3, 0
	v_readlane_b32 s3, v250, 3
	s_cmp_lg_u64 s[18:19], 0
	v_readlane_b32 s9, v250, 5
	v_lshl_add_u64 v[36:37], s[20:21], 0, v[2:3]
	v_add_u32_e32 v4, s3, v2
	s_cselect_b64 s[4:5], -1, 0
	v_mul_u32_u24_e32 v6, 0x420, v225
	v_lshl_add_u64 v[38:39], s[8:9], 0, v[2:3]
	v_lshlrev_b32_e32 v2, 2, v224
	v_mul_u32_u24_e32 v5, 0x84, v224
	v_add3_u32 v45, s3, v6, v2
	s_lshl_b32 s8, s34, 6
	v_cndmask_b32_e64 v2, 0, 1, s[4:5]
	v_or_b32_e32 v1, 8, v224
	v_or_b32_e32 v35, 16, v224
	v_or_b32_e32 v43, 24, v224
	s_lshl_b32 s3, s34, 5
	s_lshl_b32 s14, s64, 5
	s_add_i32 s15, s8, 0x7fffd400
	s_lshl_b32 s20, s64, 6
	s_mov_b32 s21, 0xb000
	v_cmp_ne_u32_e64 s[4:5], 1, v2
	v_add_u32_e32 v46, v4, v5
	s_mov_b32 s33, s34
	s_branch .LBB0_21
	.p2align	6

; #define LAS __attribute__((address_space(3)))
; template <int MODE> __device__ __forceinline__ void conv_mat(const float* W, const float* nw, int K, int N, bf16* WT, LAS float* scr, int gw, int NGW, int lane) {
;     const int nblk = N / 32, nitems = (K / 64) * nblk;
;     for (int it = gw; it < nitems; it += NGW) { const int kb = it / nblk, nb = it % nblk, n0 = 32 * nb; int d = n0;
;         if (MODE == 1) { d = (n0 < DFF) ? 256 * (n0 / 128) + (n0 % 128) : 256 * ((n0 - DFF) / 128) + 128 + ((n0 - DFF) % 128); }
;         tr_item(W, nw, K, N, WT, 64 * kb, n0, d, scr, lane); }
; __global__ void __launch_bounds__(512, 2) fwd_megakernel(Args a) {
;     ...
;     conv_mat<0>(a.in[I_F1O], nullptr, DFF, DM, WFO, scr, gw, NGW, lane);
.LBB0_33:
	s_add_u32 s68, s62, 0x2d00000
	s_addc_u32 s69, s63, 0
	s_cmpk_lt_i32 s34, 0x1600
	s_cselect_b64 s[4:5], -1, 0
	v_writelane_b32 v250, s4, 6
	s_movk_i32 s3, 0x1600
	s_cmpk_gt_i32 s34, 0x15ff
	v_writelane_b32 v250, s5, 7
	s_mul_i32 s4, s34, 0x2c000
	s_mul_i32 s11, s64, 0x2c000
	v_writelane_b32 v250, s4, 8
	s_cbranch_scc1 .LBB0_36
	v_lshlrev_b32_e32 v4, 4, v225
	v_readlane_b32 s4, v250, 3
	v_mul_u32_u24_e32 v1, 0x420, v225
	v_lshlrev_b32_e32 v6, 2, v224
	v_add_u32_e32 v7, s4, v4
	v_mul_u32_u24_e32 v8, 0x84, v224
	v_add3_u32 v1, s4, v1, v6
	s_mul_i32 s4, s34, 0x2c000
	v_mov_b32_e32 v5, 0
	v_mov_b32_e32 v6, s4
	v_add_u32_e32 v7, v7, v8
	v_lshl_add_u64 v[2:3], s[22:23], 0, v[4:5]
	v_lshl_add_u64 v[4:5], s[68:69], 0, v[4:5]
	v_mad_u32_u24 v6, v224, s3, v6
	s_lshl_b32 s3, s34, 5
	s_lshl_b32 s8, s64, 5
	v_add_u32_e32 v8, 0x420, v7
	v_add_u32_e32 v9, 0x428, v7
	v_add_u32_e32 v10, 0x840, v7
	v_add_u32_e32 v11, 0x848, v7
	v_add_u32_e32 v12, 0xc60, v7
	v_add_u32_e32 v13, 0xc68, v7
	v_add_u32_e32 v14, 0x1080, v7
	v_add_u32_e32 v15, 0x1088, v7
	v_add_u32_e32 v16, 0x14a0, v7
	v_add_u32_e32 v17, 0x14a8, v7
	v_add_u32_e32 v18, 0x18c0, v7
	v_add_u32_e32 v19, 0x18c8, v7
	v_add_u32_e32 v20, 0x1ce0, v7
	v_add_u32_e32 v21, 0x1ce8, v7
	s_mov_b32 s9, s34
	.p2align	6

; #define LAS __attribute__((address_space(3)))
; template <int MODE> __device__ __forceinline__ void conv_mat(const float* W, const float* nw, int K, int N, bf16* WT, LAS float* scr, int gw, int NGW, int lane) {
;     const int nblk = N / 32, nitems = (K / 64) * nblk;
;     for (int it = gw; it < nitems; it += NGW) { const int kb = it / nblk, nb = it % nblk, n0 = 32 * nb; int d = n0;
;         if (MODE == 1) { d = (n0 < DFF) ? 256 * (n0 / 128) + (n0 % 128) : 256 * ((n0 - DFF) / 128) + 128 + ((n0 - DFF) % 128); }
;         tr_item(W, nw, K, N, WT, 64 * kb, n0, d, scr, lane); }
; __global__ void __launch_bounds__(512, 2) fwd_megakernel(Args a) {
;     ...
;     conv_mat<0>(a.in[I_WIN], a.in[I_MIXN], DM, 11264, WIN, scr, gw, NGW, lane);
.LBB0_36:
	v_cndmask_b32_e64 v1, 0, 1, s[6:7]
	v_writelane_b32 v250, s11, 9
	s_add_u32 s18, s62, 0x4300000
	v_cmp_ne_u32_e64 s[4:5], 1, v1
	s_addc_u32 s19, s63, 0
	s_andn2_b64 vcc, exec, s[6:7]
	v_writelane_b32 v250, s4, 10
	s_nop 1
	v_writelane_b32 v250, s5, 11
	s_cbranch_vccnz .LBB0_47
	v_lshlrev_b32_e32 v2, 4, v225
	v_mov_b32_e32 v3, 0
	v_readlane_b32 s3, v250, 3
	s_cmp_lg_u64 s[24:25], 0
	v_lshl_add_u64 v[36:37], s[26:27], 0, v[2:3]
	v_add_u32_e32 v4, s3, v2
	s_cselect_b64 s[4:5], -1, 0
	v_mul_u32_u24_e32 v1, 0x420, v225
	v_lshl_add_u64 v[38:39], s[18:19], 0, v[2:3]
	v_lshlrev_b32_e32 v2, 2, v224
	v_mul_u32_u24_e32 v5, 0x84, v224
	v_add3_u32 v1, s3, v1, v2
	v_cndmask_b32_e64 v2, 0, 1, s[4:5]
	s_lshl_b32 s3, s34, 5
	s_lshl_b32 s10, s64, 5
	s_mov_b32 s11, 0xb000
	v_cmp_ne_u32_e64 s[6:7], 1, v2
	v_add_u32_e32 v35, v4, v5
	s_mov_b32 s14, s34
	s_branch .LBB0_39
	.p2align	6

; #define LAS __attribute__((address_space(3)))
; template <int MODE> __device__ __forceinline__ void conv_mat(const float* W, const float* nw, int K, int N, bf16* WT, LAS float* scr, int gw, int NGW, int lane) {
;     const int nblk = N / 32, nitems = (K / 64) * nblk;
;     for (int it = gw; it < nitems; it += NGW) { const int kb = it / nblk, nb = it % nblk, n0 = 32 * nb; int d = n0;
;         if (MODE == 1) { d = (n0 < DFF) ? 256 * (n0 / 128) + (n0 % 128) : 256 * ((n0 - DFF) / 128) + 128 + ((n0 - DFF) % 128); }
;         tr_item(W, nw, K, N, WT, 64 * kb, n0, d, scr, lane); }
; __global__ void __launch_bounds__(512, 2) fwd_megakernel(Args a) {
;     ...
;     conv_mat<0>(a.in[I_WPA], nullptr, 1024, DM, WPA, scr, gw, NGW, lane);
.LBB0_47:
	s_load_dwordx16 s[36:51], s[0:1], 0x40
	s_add_u32 s0, s62, 0x7300000
	s_addc_u32 s1, s63, 0
	s_waitcnt lgkmcnt(0)
	v_writelane_b32 v250, s36, 12
	s_nop 1
	v_writelane_b32 v250, s37, 13
	v_writelane_b32 v250, s38, 14
	v_writelane_b32 v250, s39, 15
	v_writelane_b32 v250, s40, 16
	v_writelane_b32 v250, s41, 17
	v_writelane_b32 v250, s42, 18
	v_writelane_b32 v250, s43, 19
	v_writelane_b32 v250, s44, 20
	v_writelane_b32 v250, s45, 21
	v_writelane_b32 v250, s46, 22
	v_writelane_b32 v250, s47, 23
	v_writelane_b32 v250, s48, 24
	v_writelane_b32 v250, s49, 25
	v_writelane_b32 v250, s50, 26
	v_writelane_b32 v250, s51, 27
	v_writelane_b32 v250, s0, 28
	s_nop 1
	v_writelane_b32 v250, s1, 29
	s_add_u32 s0, s62, 0x6f00000
	s_addc_u32 s1, s63, 0
	v_writelane_b32 v250, s0, 30
	s_cmpk_gt_i32 s34, 0x3ff
	s_nop 0
	v_writelane_b32 v250, s1, 31
	s_cbranch_scc1 .LBB0_52
	v_lshlrev_b32_e32 v8, 4, v225
	v_readlane_b32 s0, v250, 3
	v_readlane_b32 s36, v250, 12
	v_mul_u32_u24_e32 v5, 0x84, v224
	v_add_u32_e32 v3, s0, v8
	v_mul_u32_u24_e32 v1, 0x420, v225
	v_readlane_b32 s4, v250, 30
	v_lshlrev_b32_e32 v10, 2, v224
	v_mov_b32_e32 v9, 0
	v_readlane_b32 s46, v250, 22
	v_readlane_b32 s47, v250, 23
	v_readlane_b32 s5, v250, 31
	v_add3_u32 v1, s0, v1, v10
	s_lshl_b32 s3, s34, 5
	v_add_u32_e32 v10, v3, v5
	v_lshlrev_b32_e32 v2, 2, v225
	v_lshl_add_u64 v[6:7], s[46:47], 0, v[8:9]
	v_lshlrev_b32_e32 v4, 3, v225
	v_lshl_add_u64 v[8:9], s[4:5], 0, v[8:9]
	s_lshl_b32 s6, s64, 5
	v_add_u32_e32 v3, 0x420, v10
	v_add_u32_e32 v5, 0x428, v10
	v_add_u32_e32 v11, 0x840, v10
	v_add_u32_e32 v12, 0x848, v10
	v_add_u32_e32 v13, 0xc60, v10
	v_add_u32_e32 v14, 0xc68, v10
	v_add_u32_e32 v15, 0x1080, v10
	v_add_u32_e32 v16, 0x1088, v10
	v_add_u32_e32 v17, 0x14a0, v10
	v_add_u32_e32 v18, 0x14a8, v10
	v_add_u32_e32 v19, 0x18c0, v10
	v_add_u32_e32 v20, 0x18c8, v10
	v_add_u32_e32 v21, 0x1ce0, v10
	v_add_u32_e32 v22, 0x1ce8, v10
	s_mov_b32 s7, s3
	s_mov_b32 s8, s34
	v_readlane_b32 s37, v250, 13
	v_readlane_b32 s38, v250, 14
	v_readlane_b32 s39, v250, 15
	v_readlane_b32 s40, v250, 16
	v_readlane_b32 s41, v250, 17
	v_readlane_b32 s42, v250, 18
	v_readlane_b32 s43, v250, 19
	v_readlane_b32 s44, v250, 20
	v_readlane_b32 s45, v250, 21
	v_readlane_b32 s48, v250, 24
	v_readlane_b32 s49, v250, 25
	v_readlane_b32 s50, v250, 26
	v_readlane_b32 s51, v250, 27
	.p2align	6
; #define LAS __attribute__((address_space(3)))
; __device__ __forceinline__ unsigned pkbf(float lo, float hi) { const f32x2_m v = {lo, hi}; const bf16x2_m b = __builtin_convertvector(v, bf16x2_m); return __builtin_bit_cast(unsigned, b); }
; __device__ __forceinline__ void tr_item(const float* W, const float* nw, int K, int N, bf16* WT, int k0, int n0, int drow0, LAS float* scr, int lane) {
;     { const int r = lane >> 3, c4 = lane & 7; f32x4 v[8];
; #pragma unroll
;       for (int i = 0; i < 8; ++i) v[i] = *(const f32x4*)(W + (size_t)(k0 + 8 * i + r) * N + n0 + 4 * c4);
; #pragma unroll
;       for (int i = 0; i < 8; ++i) { LAS float* d = scr + (8 * i + r) * 33 + 4 * c4; const float s = nw ? nw[k0 + 8 * i + r] : 1.f; d[0] = v[i].x * s; d[1] = v[i].y * s; d[2] = v[i].z * s; d[3] = v[i].w * s; } }
;     asm volatile("s_waitcnt lgkmcnt(0)" ::: "memory");
;     const int c = lane & 7;
; #pragma unroll
;     for (int j = 0; j < 4; ++j) { const int n = (lane >> 3) + 8 * j; const LAS float* s = scr + (8 * c) * 33 + n;
;         v4u o; o.x = pkbf(s[0 * 33], s[1 * 33]); o.y = pkbf(s[2 * 33], s[3 * 33]); o.z = pkbf(s[4 * 33], s[5 * 33]); o.w = pkbf(s[6 * 33], s[7 * 33]);
;         *(v4u*)(WT + (size_t)(drow0 + n) * K + k0 + 8 * c) = o; }
;     asm volatile("s_waitcnt lgkmcnt(0)" ::: "memory");
; }
; template <int MODE> __device__ __forceinline__ void conv_mat(const float* W, const float* nw, int K, int N, bf16* WT, LAS float* scr, int gw, int NGW, int lane) {
;     const int nblk = N / 32, nitems = (K / 64) * nblk;
;     for (int it = gw; it < nitems; it += NGW) { const int kb = it / nblk, nb = it % nblk, n0 = 32 * nb; int d = n0;
;         if (MODE == 1) { d = (n0 < DFF) ? 256 * (n0 / 128) + (n0 % 128) : 256 * ((n0 - DFF) / 128) + 128 + ((n0 - DFF) % 128); }
;         tr_item(W, nw, K, N, WT, 64 * kb, n0, d, scr, lane); }
.LBB0_49:
	s_ashr_i32 s0, s8, 31
	s_lshr_b32 s0, s0, 26
	s_add_i32 s0, s8, s0
	s_lshl_b32 s1, s0, 5
	s_andn2_b32 s0, s0, 63
	s_and_b32 s1, s1, 0xfffff800
	v_or_b32_e32 v24, s0, v224
	s_sub_i32 s4, s7, s1
	v_or_b32_e32 v26, 8, v24
	v_or_b32_e32 v28, 16, v24
	v_or_b32_e32 v30, 24, v24
	v_or_b32_e32 v36, 40, v24
	v_or_b32_e32 v38, 48, v24
	v_or_b32_e32 v40, 56, v24
	v_ashrrev_i32_e32 v25, 31, v24
	v_or_b32_e32 v32, 32, v24
	s_ashr_i32 s5, s4, 31
	v_ashrrev_i32_e32 v27, 31, v26
	v_ashrrev_i32_e32 v29, 31, v28
	v_ashrrev_i32_e32 v31, 31, v30
	v_ashrrev_i32_e32 v37, 31, v36
	v_ashrrev_i32_e32 v39, 31, v38
	v_ashrrev_i32_e32 v41, 31, v40
	v_lshlrev_b64 v[24:25], 13, v[24:25]
	v_ashrrev_i32_e32 v33, 31, v32
	v_lshl_add_u64 v[42:43], s[4:5], 2, v[6:7]
	v_lshlrev_b64 v[26:27], 13, v[26:27]
	v_lshlrev_b64 v[28:29], 13, v[28:29]
	v_lshlrev_b64 v[30:31], 13, v[30:31]
	v_lshlrev_b64 v[36:37], 13, v[36:37]
	v_lshlrev_b64 v[38:39], 13, v[38:39]
	v_lshlrev_b64 v[40:41], 13, v[40:41]
	v_lshlrev_b64 v[32:33], 13, v[32:33]
	v_lshl_add_u64 v[24:25], v[42:43], 0, v[24:25]
	v_lshl_add_u64 v[44:45], v[42:43], 0, v[26:27]
	v_lshl_add_u64 v[46:47], v[42:43], 0, v[28:29]
	v_lshl_add_u64 v[48:49], v[42:43], 0, v[30:31]
	v_lshl_add_u64 v[50:51], v[42:43], 0, v[36:37]
	v_lshl_add_u64 v[52:53], v[42:43], 0, v[38:39]
	v_lshl_add_u64 v[56:57], v[42:43], 0, v[40:41]
	v_lshl_add_u64 v[32:33], v[42:43], 0, v[32:33]
	global_load_dwordx4 v[24:27], v[24:25], off nt
	s_nop 0
	global_load_dwordx4 v[28:31], v[44:45], off nt
	global_load_dwordx4 v[36:39], v[46:47], off nt
	global_load_dwordx4 v[40:43], v[48:49], off nt
	s_nop 0
	global_load_dwordx4 v[44:47], v[32:33], off nt
	s_nop 0
	global_load_dwordx4 v[48:51], v[50:51], off nt
	s_nop 0
	global_load_dwordx4 v[52:55], v[52:53], off nt
	s_nop 0
	global_load_dwordx4 v[56:59], v[56:57], off nt
	v_add_u32_e32 v60, s4, v224
	v_add_u32_e32 v62, 8, v60
	v_add_u32_e32 v64, 16, v60
	v_add_u32_e32 v66, 24, v60
	s_ashr_i32 s1, s0, 31
	v_ashrrev_i32_e32 v61, 31, v60
	v_ashrrev_i32_e32 v63, 31, v62
	v_ashrrev_i32_e32 v65, 31, v64
	v_ashrrev_i32_e32 v67, 31, v66
	v_lshl_add_u64 v[32:33], s[0:1], 1, v[8:9]
	v_lshlrev_b64 v[60:61], 11, v[60:61]
	v_lshlrev_b64 v[62:63], 11, v[62:63]
	v_lshlrev_b64 v[64:65], 11, v[64:65]
	v_lshlrev_b64 v[66:67], 11, v[66:67]
	v_lshl_add_u64 v[60:61], v[32:33], 0, v[60:61]
	v_lshl_add_u64 v[62:63], v[32:33], 0, v[62:63]
	v_lshl_add_u64 v[64:65], v[32:33], 0, v[64:65]
	v_lshl_add_u64 v[32:33], v[32:33], 0, v[66:67]
	s_add_i32 s8, s8, s64
	s_add_i32 s7, s7, s6
	s_cmpk_lt_i32 s8, 0x400
	s_waitcnt vmcnt(7)
	ds_write2_b32 v10, v24, v25 offset1:1
	ds_write2_b32 v10, v26, v27 offset0:2 offset1:3
	s_waitcnt vmcnt(6)
	ds_write2_b32 v3, v28, v29 offset1:1
	ds_write2_b32 v5, v30, v31 offset1:1
	s_waitcnt vmcnt(5)
	ds_write2_b32 v11, v36, v37 offset1:1
	ds_write2_b32 v12, v38, v39 offset1:1
	s_waitcnt vmcnt(4)
	ds_write2_b32 v13, v40, v41 offset1:1
	ds_write2_b32 v14, v42, v43 offset1:1
	s_waitcnt vmcnt(3)
	ds_write2_b32 v15, v44, v45 offset1:1
	ds_write2_b32 v16, v46, v47 offset1:1
	s_waitcnt vmcnt(2)
	ds_write2_b32 v17, v48, v49 offset1:1
	ds_write2_b32 v18, v50, v51 offset1:1
	s_waitcnt vmcnt(1)
	ds_write2_b32 v19, v52, v53 offset1:1
	ds_write2_b32 v20, v54, v55 offset1:1
	s_waitcnt vmcnt(0)
	ds_write2_b32 v21, v56, v57 offset1:1
	ds_write2_b32 v22, v58, v59 offset1:1
	s_waitcnt lgkmcnt(0)
	ds_read2_b32 v[28:29], v1 offset0:33 offset1:41
	ds_read2_b32 v[30:31], v1 offset1:8
	ds_read2_b32 v[36:37], v1 offset0:66 offset1:74
	ds_read2_b32 v[38:39], v1 offset0:99 offset1:107
	ds_read2_b32 v[40:41], v1 offset0:132 offset1:140
	ds_read2_b32 v[42:43], v1 offset0:165 offset1:173
	ds_read2_b32 v[44:45], v1 offset0:198 offset1:206
	ds_read2_b32 v[46:47], v1 offset0:231 offset1:239
	ds_read2_b32 v[48:49], v1 offset0:49 offset1:57
	ds_read2_b32 v[50:51], v1 offset0:16 offset1:24
	ds_read2_b32 v[52:53], v1 offset0:82 offset1:90
	ds_read2_b32 v[54:55], v1 offset0:115 offset1:123
	ds_read2_b32 v[56:57], v1 offset0:148 offset1:156
	ds_read2_b32 v[58:59], v1 offset0:181 offset1:189
	ds_read2_b32 v[66:67], v1 offset0:214 offset1:222
	ds_read2_b32 v[68:69], v1 offset0:247 offset1:255
	s_waitcnt lgkmcnt(14)
	v_cvt_pk_bf16_f32 v24, v30, v28
	s_waitcnt lgkmcnt(12)
	v_cvt_pk_bf16_f32 v25, v36, v38
	s_waitcnt lgkmcnt(10)
	v_cvt_pk_bf16_f32 v26, v40, v42
	s_waitcnt lgkmcnt(8)
	v_cvt_pk_bf16_f32 v27, v44, v46
	v_cvt_pk_bf16_f32 v28, v31, v29
	v_cvt_pk_bf16_f32 v29, v37, v39
	v_cvt_pk_bf16_f32 v30, v41, v43
	v_cvt_pk_bf16_f32 v31, v45, v47
	s_waitcnt lgkmcnt(6)
	v_cvt_pk_bf16_f32 v36, v50, v48
	s_waitcnt lgkmcnt(4)
	v_cvt_pk_bf16_f32 v37, v52, v54
	s_waitcnt lgkmcnt(2)
	v_cvt_pk_bf16_f32 v38, v56, v58
	s_waitcnt lgkmcnt(0)
	v_cvt_pk_bf16_f32 v39, v66, v68
	v_cvt_pk_bf16_f32 v40, v51, v49
	v_cvt_pk_bf16_f32 v41, v53, v55
	v_cvt_pk_bf16_f32 v42, v57, v59
	v_cvt_pk_bf16_f32 v43, v67, v69
	global_store_dwordx4 v[60:61], v[24:27], off
	global_store_dwordx4 v[62:63], v[28:31], off
	global_store_dwordx4 v[64:65], v[36:39], off
	global_store_dwordx4 v[32:33], v[40:43], off
	s_waitcnt lgkmcnt(0)
	s_cbranch_scc1 .LBB0_49
	v_readlane_b32 s36, v250, 12
	v_lshlrev_b32_e32 v6, 2, v2
	v_mov_b32_e32 v7, 0
	v_readlane_b32 s48, v250, 24
	v_readlane_b32 s49, v250, 25
	v_readlane_b32 s0, v250, 28
	v_readlane_b32 s1, v250, 29
	v_lshl_add_u64 v[2:3], s[48:49], 0, v[6:7]
	v_lshlrev_b32_e32 v6, 1, v4
	v_lshl_add_u64 v[4:5], s[0:1], 0, v[6:7]
	s_mov_b32 s7, s34
	v_readlane_b32 s37, v250, 13
	v_readlane_b32 s38, v250, 14
	v_readlane_b32 s39, v250, 15
	v_readlane_b32 s40, v250, 16
	v_readlane_b32 s41, v250, 17
	v_readlane_b32 s42, v250, 18
	v_readlane_b32 s43, v250, 19
	v_readlane_b32 s44, v250, 20
	v_readlane_b32 s45, v250, 21
	v_readlane_b32 s46, v250, 22
	v_readlane_b32 s47, v250, 23
	v_readlane_b32 s50, v250, 26
	v_readlane_b32 s51, v250, 27
	.p2align	6

; #define LAS __attribute__((address_space(3)))
; template <int MODE> __device__ __forceinline__ void conv_mat(const float* W, const float* nw, int K, int N, bf16* WT, LAS float* scr, int gw, int NGW, int lane) {
;     const int nblk = N / 32, nitems = (K / 64) * nblk;
;     for (int it = gw; it < nitems; it += NGW) { const int kb = it / nblk, nb = it % nblk, n0 = 32 * nb; int d = n0;
;         if (MODE == 1) { d = (n0 < DFF) ? 256 * (n0 / 128) + (n0 % 128) : 256 * ((n0 - DFF) / 128) + 128 + ((n0 - DFF) % 128); }
;         tr_item(W, nw, K, N, WT, 64 * kb, n0, d, scr, lane); }
; __global__ void __launch_bounds__(512, 2) fwd_megakernel(Args a) {
;     ...
;     conv_mat<0>(a.in[I_WOUT], nullptr, DM, DM, WWO, scr, gw, NGW, lane);
.LBB0_52:
	s_add_u32 s0, s62, 0x7700000
	s_addc_u32 s1, s63, 0
	v_writelane_b32 v250, s0, 32
	s_cmpk_gt_i32 s34, 0x7ff
	s_nop 0
	v_writelane_b32 v250, s1, 33
	s_cbranch_scc1 .LBB0_55
	v_lshlrev_b32_e32 v4, 4, v225
	v_readlane_b32 s3, v250, 3
	v_readlane_b32 s36, v250, 12
	v_mul_u32_u24_e32 v7, 0x84, v224
	v_add_u32_e32 v6, s3, v4
	v_readlane_b32 s0, v250, 32
	v_mov_b32_e32 v5, 0
	v_readlane_b32 s50, v250, 26
	v_readlane_b32 s51, v250, 27
	v_mul_u32_u24_e32 v1, 0x420, v225
	v_readlane_b32 s1, v250, 33
	v_lshlrev_b32_e32 v8, 2, v224
	v_add_u32_e32 v6, v6, v7
	v_lshl_add_u64 v[2:3], s[50:51], 0, v[4:5]
	v_lshl_add_u64 v[4:5], s[0:1], 0, v[4:5]
	v_add3_u32 v1, s3, v1, v8
	s_lshl_b32 s3, s34, 5
	s_lshl_b32 s6, s64, 5
	v_add_u32_e32 v7, 0x420, v6
	v_add_u32_e32 v8, 0x428, v6
	v_add_u32_e32 v9, 0x840, v6
	v_add_u32_e32 v10, 0x848, v6
	v_add_u32_e32 v11, 0xc60, v6
	v_add_u32_e32 v12, 0xc68, v6
	v_add_u32_e32 v13, 0x1080, v6
	v_add_u32_e32 v14, 0x1088, v6
	v_add_u32_e32 v15, 0x14a0, v6
	v_add_u32_e32 v16, 0x14a8, v6
	v_add_u32_e32 v17, 0x18c0, v6
	v_add_u32_e32 v18, 0x18c8, v6
	v_add_u32_e32 v19, 0x1ce0, v6
	v_add_u32_e32 v20, 0x1ce8, v6
	s_mov_b32 s7, s34
	v_readlane_b32 s37, v250, 13
	v_readlane_b32 s38, v250, 14
	v_readlane_b32 s39, v250, 15
	v_readlane_b32 s40, v250, 16
	v_readlane_b32 s41, v250, 17
	v_readlane_b32 s42, v250, 18
	v_readlane_b32 s43, v250, 19
	v_readlane_b32 s44, v250, 20
	v_readlane_b32 s45, v250, 21
	v_readlane_b32 s46, v250, 22
	v_readlane_b32 s47, v250, 23
	v_readlane_b32 s48, v250, 24
	v_readlane_b32 s49, v250, 25
	.p2align	6

; __device__ __forceinline__ void prep_rows_bf16(const float* X, float* rs, bf16* Hout, int gw, int NGW, int lane) {
;     for (int m = gw; m < M; m += NGW) { const f32x4* xr = (const f32x4*)(X + (size_t)m * DM) + lane; f32x4 v[8]; float s = 0.f;
; #pragma unroll
;         for (int j = 0; j < 8; ++j) { v[j] = xr[64 * j]; s += (v[j].x * v[j].x + v[j].y * v[j].y) + (v[j].z * v[j].z + v[j].w * v[j].w); }
;         const float rstd = 1.0f / sqrtf(wave_sum(s) * (1.f / DM) + EPS);
;         if (lane == 0) rs[m] = rstd;
;         v2u* o = (v2u*)(Hout + (size_t)m * DM) + lane;
.LBB0_66:
	s_or_b64 exec, exec, s[4:5]
	s_cmpk_lt_i32 s34, 0x4000
	s_cselect_b64 s[0:1], -1, 0
	v_writelane_b32 v250, s0, 34
	s_cmpk_gt_i32 s34, 0x3fff
	v_mbcnt_lo_u32_b32 v226, -1, 0
	v_writelane_b32 v250, s1, 35
	s_cbranch_scc1 .LBB0_71
	v_mbcnt_hi_u32_b32 v2, -1, v226
	v_and_b32_e32 v1, 64, v2
	v_add_u32_e32 v3, 64, v1
	v_xor_b32_e32 v1, 1, v2
	v_cmp_lt_i32_e32 vcc, v1, v3
	v_xor_b32_e32 v4, 2, v2
	s_ashr_i32 s35, s34, 31
	v_cndmask_b32_e32 v1, v2, v1, vcc
	v_cmp_lt_i32_e32 vcc, v4, v3
	s_lshl_b64 s[4:5], s[34:35], 2
	s_add_u32 s3, s4, 0x50000
	v_cndmask_b32_e32 v4, v2, v4, vcc
	v_lshlrev_b32_e32 v40, 2, v4
	v_xor_b32_e32 v4, 4, v2
	v_cmp_lt_i32_e32 vcc, v4, v3
	s_addc_u32 s20, s5, 0
	s_ashr_i32 s65, s64, 31
	v_cndmask_b32_e32 v4, v2, v4, vcc
	v_lshlrev_b32_e32 v41, 2, v4
	v_xor_b32_e32 v4, 8, v2
	v_cmp_lt_i32_e32 vcc, v4, v3
	s_lshl_b64 s[4:5], s[64:65], 2
	s_lshl_b64 s[6:7], s[34:35], 13
	v_cndmask_b32_e32 v4, v2, v4, vcc
	v_lshlrev_b32_e32 v42, 2, v4
	v_xor_b32_e32 v4, 16, v2
	v_cmp_lt_i32_e32 vcc, v4, v3
	s_add_u32 s6, s16, s6
	v_lshlrev_b32_e32 v34, 4, v223
	v_cndmask_b32_e32 v4, v2, v4, vcc
	v_lshlrev_b32_e32 v43, 2, v4
	v_xor_b32_e32 v4, 32, v2
	v_cmp_lt_i32_e32 vcc, v4, v3
	v_mov_b32_e32 v35, 0
	s_addc_u32 s7, s17, s7
	v_cndmask_b32_e32 v2, v2, v4, vcc
	v_lshlrev_b32_e32 v44, 2, v2
	v_lshl_add_u64 v[2:3], s[6:7], 0, v[34:35]
	s_mov_b64 s[6:7], 0x1000
	v_lshl_add_u64 v[36:37], v[2:3], 0, s[6:7]
	s_lshl_b64 s[6:7], s[34:35], 12
	v_lshlrev_b32_e32 v1, 2, v1
	v_cmp_eq_u32_e64 s[0:1], 0, v223
	s_lshl_b64 s[8:9], s[64:65], 13
	v_lshl_or_b32 v38, v223, 3, s6
	v_mov_b32_e32 v39, s7
	s_lshl_b64 s[10:11], s[64:65], 12
	v_mov_b32_e32 v34, 0x358637bd
	s_mov_b32 s21, 0xf800000
	v_mov_b32_e32 v45, 0x260
	s_mov_b32 s22, s34
	s_branch .LBB0_69
	.p2align	6

;   #define RESC() do{ if(resc){ asm volatile("s_waitcnt lgkmcnt(0)":::"memory"); \
;       _Pragma("unroll") for(int d_=0;d_<2;++d_) _Pragma("unroll") for(int r=0;r<16;++r)o[d_][r]*=wsf[crow(r,hi)]; } }while(0)
;   #define ROT() do{sl_prev=sl_cur;sl_cur=sl_next;sl_next=(sl_next==(NSLOT-1)*SLOTB)?0:sl_next+SLOTB;}while(0)
;   #define ENDW(tt) do{ if((tt)+3<NT){WAIT_BAR(2);} else if((tt)+2<NT){WAIT_BAR(1);} else {WAIT_BAR(0);} }while(0)
; template<int THRL> __device__ __forceinline__ void attn_unit(int b,int h,int hv,int qb,const bf16*Q,const bf16*__restrict__ K,const bf16*__restrict__ V,bf16*O,char*shm){
;     ...
;   for(;t+1<NT;t+=2){
;     STEP(pB0,pB1,pA0,pA1,t,(t+3<NT),(t+1<NT),(t+1<NT));       ENDW(t);   RESC(); ROT();
;     STEP(pA0,pA1,pB0,pB1,t+1,(t+4<NT),(t+2<NT),(t+2<NT));     ENDW(t+1); RESC(); ROT();
.LBB0_1442:
	s_xor_b64 s[20:21], s[10:11], -1
	s_lshl_b64 s[22:23], s[22:23], 10
	s_add_i32 s0, s42, 1
	s_cmp_ge_u32 s0, s3
	s_cbranch_scc1 .LBB0_1493
	s_lshl_b32 s0, s42, 6
	s_addk_i32 s0, 0x7b
	v_add_u32_e32 v0, s0, v235
	s_lshl_b32 s0, s24, 2
	s_sub_i32 s77, 0, s0
	s_lshl_b64 s[0:1], s[42:43], 17
	v_lshl_add_u64 v[14:15], v[214:215], 0, s[0:1]
	v_lshl_add_u64 v[2:3], v[212:213], 0, s[0:1]
	s_mov_b64 s[0:1], 0x80000
	v_cmp_gt_u32_e64 s[8:9], 32, v229
	v_subrev_u32_e32 v0, s25, v0
	s_add_i32 s24, s42, 2
	v_lshl_add_u64 v[220:221], v[2:3], 0, s[0:1]
	.p2align	6

; #define LAS __attribute__((address_space(3)))
; #define HG_BAR() asm volatile("s_waitcnt lgkmcnt(0)\n\ts_barrier" ::: "memory")
; __device__ __forceinline__ void hgrn_unit(LAS unsigned char* lds, int b, int h, int vs, const bf16* QR, const _Float16* LF, const bf16* IO, bf16* OR_) {
;     ...
;     } else {
;         const int mw = wid - 4;
;         for (int i = tid - 256; i < 32 * QS / 2; i += 256) ((LAS unsigned*)(lds + OFF_ST))[i] = 0u;
;         f32x4 sacc[2][2];
; #pragma unroll
;         for (int ki = 0; ki < 2; ++ki)
; #pragma unroll
;             for (int vj = 0; vj < 2; ++vj) sacc[ki][vj] = (f32x4){0.f, 0.f, 0.f, 0.f};
;         bf16* op = OR_ + (rowbase + 16 * mw + fr) * 1024 + h * 128 + vs * 32 + 4 * fq;
;         HG_BAR(); HG_BAR();
;         for (int c = 0; c < NCH; ++c) {
;             bf16x8 qgf[4], knf[4][4], stf[2][4], vtf[2][2], klf[2][2]; f32x4 glv[2];
.LBB0_1506:
	s_or_b64 exec, exec, s[0:1]
	s_add_i32 s0, s3, -4
	s_and_b32 s1, s68, 3
	s_and_b32 s18, s38, 7
	s_lshl_b32 s19, s1, 6
	s_lshl_b32 s1, s0, 4
	s_lshl_b32 s8, s0, 5
	s_cmp_lg_u32 s3, 4
	v_and_b32_e32 v0, 15, v184
	v_lshrrev_b32_e32 v2, 2, v184
	s_cselect_b64 s[50:51], -1, 0
	s_cmp_gt_u32 s3, 5
	v_and_b32_e32 v2, 12, v2
	v_or_b32_e32 v3, s1, v0
	s_movk_i32 s10, 0x110
	s_movk_i32 s9, 0x48
	s_cselect_b64 s[88:89], -1, 0
	s_cmp_gt_u32 s3, 6
	v_mul_lo_u32 v5, v3, s10
	v_mul_lo_u32 v6, v3, s9
	v_mul_lo_u32 v7, v3, s33
	v_or_b32_e32 v3, s8, v2
	s_cselect_b64 s[90:91], -1, 0
	v_or_b32_e32 v10, s8, v0
	s_or_b32 s8, s8, 16
	s_cmp_eq_u32 s0, 0
	v_or_b32_e32 v11, s8, v2
	v_or_b32_e32 v12, s8, v0
	s_cselect_b64 s[8:9], -1, 0
	s_cmp_eq_u32 s0, 1
	s_cselect_b64 s[92:93], -1, 0
	s_cmp_eq_u32 s0, 2
	v_and_b32_e32 v4, 48, v184
	v_or_b32_e32 v13, 2, v2
	s_cselect_b64 s[94:95], -1, 0
	s_cmp_eq_u32 s0, 3
	v_add_u32_e32 v4, 0, v4
	v_cmp_gt_u32_e64 s[14:15], v13, v0
	v_or_b32_e32 v13, 3, v2
	s_cselect_b64 s[96:97], -1, 0
	s_movk_i32 s20, 0x88
	s_cmp_gt_u32 s0, 1
	v_mad_u32_u24 v185, v0, s10, v4
	v_cmp_gt_u32_e64 s[10:11], v2, v0
	v_cmp_lt_u32_e64 s[12:13], v2, v0
	v_cmp_gt_u32_e64 s[16:17], v13, v0
	v_add_lshl_u32 v6, v6, v2, 1
	v_mul_u32_u24_e32 v2, 0x88, v0
	v_mad_u32_u24 v13, v0, s20, v228
	s_cselect_b64 s[24:25], -1, 0
	s_add_u32 s0, s86, s1
	v_lshlrev_b32_e32 v9, 2, v3
	v_add_lshl_u32 v195, v3, v2, 1
	v_add_lshl_u32 v196, v3, v13, 1
	v_or_b32_e32 v3, 16, v3
	s_addc_u32 s1, s87, 0
	v_add_lshl_u32 v197, v3, v2, 1
	v_add_lshl_u32 v198, v3, v13, 1
	v_lshl_add_u64 v[2:3], s[0:1], 0, v[0:1]
	v_lshlrev_b64 v[2:3], 11, v[2:3]
	v_mul_u32_u24_e32 v8, 0x90, v0
	v_lshl_or_b32 v0, s18, 8, v2
	v_lshrrev_b32_e32 v2, 1, v184
	s_waitcnt lgkmcnt(0)
	s_barrier
	v_and_b32_e32 v2, 24, v2
	s_waitcnt lgkmcnt(0)
	s_barrier
	v_or3_b32 v2, v0, s19, v2
	v_mul_lo_u32 v10, v10, s33
	v_lshlrev_b32_e32 v11, 2, v11
	v_mul_lo_u32 v12, v12, s33
	v_lshl_add_u64 v[14:15], s[62:63], 0, v[2:3]
	v_mov_b32_e32 v2, 0
	v_add_u32_e32 v186, 0x1100, v185
	v_add_u32_e32 v187, 0x10600, v185
	v_add_u32_e32 v188, 0x10640, v185
	v_add_u32_e32 v189, 0x10680, v185
	v_add_u32_e32 v190, 0x106c0, v185
	v_add_u32_e32 v191, 0x11700, v185
	v_add_u32_e32 v192, 0x11740, v185
	v_add_u32_e32 v193, 0x11780, v185
	v_add_u32_e32 v194, 0x117c0, v185
	s_mov_b64 s[0:1], 0
	v_add_u32_e32 v0, v4, v5
	v_add_u32_e32 v199, v4, v8
	v_add_u32_e32 v200, s72, v9
	v_add_u32_e32 v201, v4, v10
	v_add_u32_e32 v202, s72, v11
	v_add_u32_e32 v203, v4, v12
	v_add_u32_e32 v204, 0, v6
	v_add_u32_e32 v205, v4, v7
	v_mov_b32_e32 v3, v2
	v_mov_b32_e32 v4, v2
	v_mov_b32_e32 v5, v2
	v_mov_b32_e32 v6, v2
	v_mov_b32_e32 v7, v2
	v_mov_b32_e32 v8, v2
	v_mov_b32_e32 v9, v2
	v_mov_b32_e32 v10, v2
	v_mov_b32_e32 v11, v2
	v_mov_b32_e32 v12, v2
	v_mov_b32_e32 v13, v2
	v_mov_b32_e32 v32, v2
	v_mov_b32_e32 v33, v2
	v_mov_b32_e32 v34, v2
	v_mov_b32_e32 v35, v2
	s_branch .LBB0_1508
	.p2align	6

; __device__ __forceinline__ void hgrn_unit(LAS unsigned char* lds, int b, int h, int vs, const bf16* QR, const _Float16* LF, const bf16* IO, bf16* OR_) {
;     ...
;     if (wid < 4) {
;         const int ew = wid, t0 = 16 * ew;
;         const unsigned* lp = (const unsigned*)(LF + (rowbase + t0) * 1024 + h * 128) + lane;
;         const unsigned* qp = (const unsigned*)(QR + (rowbase + t0) * 1024 + h * 128) + lane;
;         const int et = ew * 64 + lane, vrow = et >> 2, c8 = et & 3;
;         const v4u* vp = (const v4u*)(IO + (rowbase + vrow) * 1024 + h * 128 + vs * 32 + 8 * c8);
;         unsigned clf[16], cq[16], nlf[16], nq[16]; v4u cv, nv;
; #pragma unroll
;         for (int i = 0; i < 16; ++i) { clf[i] = lp[i * 512]; cq[i] = qp[i * 512]; nlf[i] = 0u; nq[i] = 0u; }
;         cv = *vp; nv = cv;
.LBB0_1546:
	s_and_b64 vcc, exec, s[0:1]
	s_cbranch_vccz .LBB0_1415
	s_mov_b64 s[98:99], 0x1000
	s_lshl_b32 s0, s3, 4
	s_ashr_i32 s1, s0, 31
	s_add_u32 s8, s86, s0
	s_addc_u32 s9, s87, s1
	s_lshl_b64 s[8:9], s[8:9], 11
	s_add_u32 s1, s55, s8
	s_addc_u32 s11, s56, s9
	s_lshl_b32 s42, s37, 8
	s_add_u32 s10, s1, s42
	s_addc_u32 s11, s11, 0
	s_add_u32 s1, s57, s8
	s_addc_u32 s9, s58, s9
	s_add_u32 s8, s1, s42
	v_mov_b32_e32 v2, s39
	s_movk_i32 s1, 0xffc0
	v_and_b32_e32 v34, 63, v184
	v_bfi_b32 v36, s1, v2, v184
	v_lshlrev_b32_e32 v0, 2, v34
	v_ashrrev_i32_e32 v6, 2, v36
	v_lshl_add_u64 v[10:11], s[10:11], 0, v[0:1]
	v_ashrrev_i32_e32 v7, 31, v6
	v_lshlrev_b32_e32 v4, 3, v184
	s_movk_i32 s1, 0x1000
	v_lshl_add_u64 v[2:3], s[86:87], 0, v[6:7]
	v_and_b32_e32 v7, 24, v4
	v_add_co_u32_e32 v4, vcc, s1, v10
	s_addc_u32 s9, s9, 0
	s_nop 0
	v_addc_co_u32_e32 v5, vcc, 0, v11, vcc
	v_add_co_u32_e32 v8, vcc, s49, v10
	v_lshl_add_u64 v[12:13], s[8:9], 0, v[0:1]
	s_nop 0
	v_addc_co_u32_e32 v9, vcc, 0, v11, vcc
	v_add_co_u32_e32 v14, vcc, s1, v12
	global_load_dword v41, v0, s[10:11]
	global_load_dword v39, v0, s[8:9]
	global_load_dword v43, v0, s[10:11] offset:2048
	global_load_dword v37, v0, s[8:9] offset:2048
	v_addc_co_u32_e32 v15, vcc, 0, v13, vcc
	v_add_co_u32_e32 v32, vcc, s49, v12
	s_movk_i32 s8, 0x3000
	s_nop 0
	v_addc_co_u32_e32 v33, vcc, 0, v13, vcc
	global_load_dword v47, v[8:9], off offset:-4096
	global_load_dword v53, v[32:33], off offset:-4096
	global_load_dword v51, v[4:5], off offset:2048
	global_load_dword v54, v[14:15], off offset:2048
	global_load_dword v49, v[8:9], off
	global_load_dword v35, v[32:33], off
	global_load_dword v45, v[8:9], off offset:2048
	s_nop 0
	global_load_dword v33, v[32:33], off offset:2048
	v_add_co_u32_e32 v4, vcc, s8, v10
	s_movk_i32 s1, 0x4000
	s_nop 0
	v_addc_co_u32_e32 v5, vcc, 0, v11, vcc
	v_add_co_u32_e32 v8, vcc, s1, v10
	v_lshlrev_b64 v[2:3], 11, v[2:3]
	s_nop 0
	v_addc_co_u32_e32 v9, vcc, 0, v11, vcc
	v_add_co_u32_e32 v14, vcc, s8, v12
	global_load_dword v55, v[8:9], off offset:-4096
	s_nop 0
	v_addc_co_u32_e32 v15, vcc, 0, v13, vcc
	v_add_co_u32_e32 v60, vcc, s1, v12
	s_movk_i32 s1, 0x5000
	s_nop 0
	v_addc_co_u32_e32 v61, vcc, 0, v13, vcc
	s_waitcnt lgkmcnt(4)
	global_load_dword v56, v[60:61], off offset:-4096
	global_load_dword v58, v[4:5], off offset:2048
	global_load_dword v57, v[14:15], off offset:2048
	global_load_dword v63, v[8:9], off
	global_load_dword v65, v[60:61], off
	global_load_dword v59, v[8:9], off offset:2048
	global_load_dword v66, v[60:61], off offset:2048
	v_add_co_u32_e32 v4, vcc, s1, v10
	v_lshl_add_u64 v[2:3], s[4:5], 0, v[2:3]
	s_nop 0
	v_addc_co_u32_e32 v5, vcc, 0, v11, vcc
	v_add_co_u32_e32 v8, vcc, s48, v10
	v_lshl_add_u64 v[2:3], v[2:3], 0, s[42:43]
	s_nop 0
	v_addc_co_u32_e32 v9, vcc, 0, v11, vcc
	v_add_co_u32_e32 v14, vcc, s1, v12
	global_load_dword v64, v[8:9], off offset:-4096
	s_nop 0
	v_addc_co_u32_e32 v15, vcc, 0, v13, vcc
	v_add_co_u32_e32 v60, vcc, s48, v12
	s_lshl_b32 s42, s36, 6
	s_nop 0
	v_addc_co_u32_e32 v61, vcc, 0, v13, vcc
	global_load_dword v71, v[60:61], off offset:-4096
	global_load_dword v70, v[4:5], off offset:2048
	global_load_dword v72, v[14:15], off offset:2048
	global_load_dword v69, v[8:9], off
	global_load_dword v73, v[60:61], off
	global_load_dword v67, v[8:9], off offset:2048
	global_load_dword v74, v[60:61], off offset:2048
	v_add_co_u32_e32 v4, vcc, s78, v10
	v_lshl_add_u64 v[2:3], v[2:3], 0, s[42:43]
	s_nop 0
	v_addc_co_u32_e32 v5, vcc, 0, v11, vcc
	v_add_co_u32_e32 v8, vcc, s78, v12
	v_lshlrev_b32_e32 v0, 1, v7
	s_nop 0
	v_addc_co_u32_e32 v9, vcc, 0, v13, vcc
	global_load_dword v68, v[4:5], off
	global_load_dword v75, v[8:9], off
	global_load_dword v81, v[4:5], off offset:2048
	global_load_dword v62, v[8:9], off offset:2048
	v_lshl_add_u64 v[14:15], v[2:3], 0, v[0:1]
	global_load_dwordx4 v[2:5], v[14:15], off
	s_cmp_gt_i32 s3, 0
	s_cselect_b64 s[8:9], -1, 0
	s_cmp_gt_i32 s3, 1
	v_lshlrev_b32_e32 v8, 3, v34
	s_cselect_b64 s[10:11], -1, 0
	s_cmp_eq_u32 s3, 3
	s_mulk_i32 s3, 0x440
	v_add_u32_e32 v110, s79, v8
	v_add_u32_e32 v111, s72, v8
	v_or_b32_e32 v8, s3, v34
	v_lshl_add_u32 v112, v8, 2, 0
	v_mul_u32_u24_e32 v8, 0x90, v34
	v_lshl_add_u32 v6, v6, 1, 0
	s_cselect_b64 s[12:13], -1, 0
	s_cmp_lt_u32 s39, 64
	v_mul_u32_u24_e32 v7, 0x90, v7
	v_add_lshl_u32 v8, s0, v8, 1
	v_lshl_add_u32 v0, v36, 3, s79
	s_cselect_b64 s[14:15], -1, 0
	v_mov_b32_e32 v115, 0
	s_mov_b32 s0, 32
	v_add_u32_e32 v113, 0, v8
	v_add_u32_e32 v114, v6, v7
	v_mov_b32_e32 v116, 0
	v_mov_b32_e32 v119, 0
	v_mov_b32_e32 v120, 0
	v_mov_b32_e32 v123, 0
	v_mov_b32_e32 v124, 0
	v_mov_b32_e32 v127, 0
	v_mov_b32_e32 v128, 0
	v_mov_b32_e32 v131, 0
	v_mov_b32_e32 v132, 0
	v_mov_b32_e32 v135, 0
	v_mov_b32_e32 v136, 0
	v_mov_b32_e32 v139, 0
	v_mov_b32_e32 v140, 0
	v_mov_b32_e32 v143, 0
	v_mov_b32_e32 v144, 0
	v_mov_b32_e32 v117, 0
	v_mov_b32_e32 v118, 0
	v_mov_b32_e32 v121, 0
	v_mov_b32_e32 v122, 0
	v_mov_b32_e32 v125, 0
	v_mov_b32_e32 v126, 0
	v_mov_b32_e32 v129, 0
	v_mov_b32_e32 v130, 0
	v_mov_b32_e32 v133, 0
	v_mov_b32_e32 v134, 0
	v_mov_b32_e32 v137, 0
	v_mov_b32_e32 v138, 0
	v_mov_b32_e32 v141, 0
	v_mov_b32_e32 v142, 0
	v_mov_b32_e32 v145, 0
	v_mov_b32_e32 v146, 0
	s_branch .LBB0_1549
	.p2align	6

; __device__ __forceinline__ float fexp(float x) { return __builtin_amdgcn_exp2f(x * LOG2E); }
; __device__ __forceinline__ void combine_rows(const bf16* O1, const bf16* O2, const bf16* OR_, const bf16* Gs, bf16* YA, bf16* YR, float lam, const float* subln, const float* gnorm, int gw, int NGW, int lane) {
;     float wa[16], wg[16];
; #pragma unroll
;     for (int i = 0; i < 16; ++i) { wa[i] = subln[16 * (lane & 7) + i] * 0.8f; wg[i] = gnorm[16 * (lane & 7) + i]; }
;     for (int m = gw; m < M; m += NGW) { const size_t p = (size_t)m * 1024 + 16 * lane;
; __global__ void __launch_bounds__(512, 2) fwd_megakernel(Args a) {
;     ...
;     { const float d1 = wave_sum(a.in[I_LQ1][lane] * a.in[I_LK1][lane]), d2 = wave_sum(a.in[I_LQ2][lane] * a.in[I_LK2][lane]);
;       const float lam = fexp(d1) - fexp(d2) + 0.2f;
;       combine_rows(O1, O2, (const bf16*)(ws + WS_OR), P + PB_G * PBUF, YA, YR, lam, a.in[I_SUBLN], a.in[I_GNORM], gw, NGW, lane); }
.LBB0_1606:
	s_or_b64 exec, exec, s[4:5]
	v_readlane_b32 s8, v250, 12
	s_waitcnt lgkmcnt(0)
	v_lshlrev_b32_e32 v0, 2, v223
	v_readlane_b32 s9, v250, 13
	s_barrier
	global_load_dword v1, v0, s[28:29]
	global_load_dword v2, v0, s[30:31]
	v_readlane_b32 s10, v250, 14
	v_readlane_b32 s11, v250, 15
	global_load_dword v3, v0, s[8:9]
	s_nop 3
	global_load_dword v0, v0, s[10:11]
	v_mbcnt_hi_u32_b32 v4, -1, v226
	v_and_b32_e32 v5, 64, v4
	v_xor_b32_e32 v6, 1, v4
	v_add_u32_e32 v5, 64, v5
	v_cmp_lt_i32_e32 vcc, v6, v5
	v_xor_b32_e32 v7, 2, v4
	v_xor_b32_e32 v8, 4, v4
	v_cndmask_b32_e32 v6, v4, v6, vcc
	v_lshlrev_b32_e32 v54, 2, v6
	v_cmp_lt_i32_e32 vcc, v7, v5
	v_xor_b32_e32 v9, 8, v4
	v_xor_b32_e32 v10, 16, v4
	v_cndmask_b32_e32 v7, v4, v7, vcc
	v_lshlrev_b32_e32 v55, 2, v7
	v_cmp_lt_i32_e32 vcc, v8, v5
	v_xor_b32_e32 v11, 32, v4
	v_readlane_b32 s0, v250, 34
	v_readlane_b32 s1, v250, 35
	v_readlane_b32 s68, v250, 53
	v_readlane_b32 s12, v250, 16
	v_readlane_b32 s13, v250, 17
	v_readlane_b32 s16, v250, 20
	v_readlane_b32 s17, v250, 21
	v_mov_b32_e32 v17, 0
	v_readlane_b32 s69, v250, 54
	v_readlane_b32 s14, v250, 18
	v_readlane_b32 s15, v250, 19
	v_readlane_b32 s18, v250, 22
	v_readlane_b32 s19, v250, 23
	v_readlane_b32 s20, v250, 24
	v_readlane_b32 s21, v250, 25
	v_readlane_b32 s22, v250, 26
	v_readlane_b32 s23, v250, 27
	s_waitcnt vmcnt(2)
	v_mul_f32_e32 v6, v1, v2
	ds_bpermute_b32 v6, v54, v6
	s_waitcnt vmcnt(0)
	v_mul_f32_e32 v12, v3, v0
	ds_bpermute_b32 v12, v54, v12
	s_waitcnt lgkmcnt(1)
	v_fmac_f32_e32 v6, v1, v2
	v_cndmask_b32_e32 v2, v4, v8, vcc
	v_lshlrev_b32_e32 v56, 2, v2
	s_waitcnt lgkmcnt(0)
	v_fmac_f32_e32 v12, v3, v0
	ds_bpermute_b32 v0, v55, v6
	ds_bpermute_b32 v1, v55, v12
	v_cmp_lt_i32_e32 vcc, v9, v5
	s_waitcnt lgkmcnt(1)
	v_add_f32_e32 v0, v6, v0
	s_waitcnt lgkmcnt(0)
	v_add_f32_e32 v1, v12, v1
	ds_bpermute_b32 v2, v56, v0
	ds_bpermute_b32 v3, v56, v1
	v_cndmask_b32_e32 v6, v4, v9, vcc
	v_lshlrev_b32_e32 v6, 2, v6
	v_cmp_lt_i32_e32 vcc, v10, v5
	s_waitcnt lgkmcnt(1)
	v_add_f32_e32 v0, v0, v2
	s_waitcnt lgkmcnt(0)
	v_add_f32_e32 v1, v1, v3
	ds_bpermute_b32 v2, v6, v0
	ds_bpermute_b32 v3, v6, v1
	v_cndmask_b32_e32 v6, v4, v10, vcc
	v_lshlrev_b32_e32 v226, 2, v6
	v_cmp_lt_i32_e32 vcc, v11, v5
	s_waitcnt lgkmcnt(1)
	v_add_f32_e32 v0, v0, v2
	s_waitcnt lgkmcnt(0)
	v_add_f32_e32 v1, v1, v3
	ds_bpermute_b32 v2, v226, v0
	ds_bpermute_b32 v3, v226, v1
	v_cndmask_b32_e32 v4, v4, v11, vcc
	v_lshlrev_b32_e32 v227, 2, v4
	s_andn2_b64 vcc, exec, s[0:1]
	s_waitcnt lgkmcnt(1)
	v_add_f32_e32 v18, v0, v2
	s_waitcnt lgkmcnt(0)
	v_add_f32_e32 v16, v1, v3
	ds_bpermute_b32 v20, v227, v18
	ds_bpermute_b32 v19, v227, v16
	v_cndmask_b32_e64 v0, 0, 1, s[0:1]
	v_cmp_ne_u32_e64 s[8:9], 1, v0
	s_cbranch_vccnz .LBB0_1609
	v_lshlrev_b32_e32 v0, 6, v223
	v_and_b32_e32 v12, 0x1c0, v0
	global_load_dwordx4 v[28:31], v12, s[12:13]
	global_load_dwordx4 v[32:35], v12, s[12:13] offset:16
	global_load_dwordx4 v[36:39], v12, s[12:13] offset:32
	global_load_dwordx4 v[40:43], v12, s[12:13] offset:48
	global_load_dwordx4 v[0:3], v12, s[16:17] offset:48
	global_load_dwordx4 v[4:7], v12, s[16:17] offset:32
	global_load_dwordx4 v[8:11], v12, s[16:17] offset:16
	s_nop 0
	global_load_dwordx4 v[12:15], v12, s[16:17]
	s_waitcnt lgkmcnt(1)
	v_add_f32_e32 v18, v18, v20
	s_waitcnt lgkmcnt(0)
	v_add_f32_e32 v19, v16, v19
	s_ashr_i32 s35, s34, 31
	v_mul_f32_e32 v18, 0x3fb8aa3b, v18
	v_mul_f32_e32 v19, 0x3fb8aa3b, v19
	s_lshl_b64 s[16:17], s[34:35], 11
	v_exp_f32_e32 v18, v18
	v_exp_f32_e32 v19, v19
	s_add_u32 s16, s62, s16
	v_lshlrev_b32_e32 v16, 5, v223
	s_addc_u32 s17, s63, s17
	s_mov_b64 s[12:13], 0x1df00010
	v_lshl_add_u64 v[16:17], s[16:17], 0, v[16:17]
	v_lshl_add_u64 v[24:25], v[16:17], 0, s[12:13]
	v_sub_f32_e32 v16, v18, v19
	s_mov_b32 s10, 0x3f4ccccd
	s_mov_b32 s0, 0xfbfffff0
	s_mov_b32 s4, 0xfdfffff0
	s_mov_b32 s14, 0xf9fffff0
	s_ashr_i32 s65, s64, 31
	v_add_f32_e32 v26, 0x3e4ccccd, v16
	s_mov_b32 s1, -1
	s_mov_b32 s5, -1
	s_mov_b32 s3, 0xfe000000
	s_mov_b32 s15, -1
	s_mov_b32 s18, 0xfa000000
	v_mov_b32_e32 v57, 0x358637bd
	s_mov_b32 s19, 0xf800000
	v_mov_b32_e32 v58, 0x260
	s_mov_b32 s20, 0xee000000
	s_brev_b32 s21, 15
	s_lshl_b64 s[16:17], s[64:65], 11
	v_mov_b32_e32 v27, v26
	s_mov_b32 s22, s34
	s_waitcnt vmcnt(7)
	v_pk_mul_f32 v[28:29], v[28:29], s[10:11] op_sel_hi:[1,0]
	v_pk_mul_f32 v[30:31], v[30:31], s[10:11] op_sel_hi:[1,0]
	s_waitcnt vmcnt(6)
	v_pk_mul_f32 v[32:33], v[32:33], s[10:11] op_sel_hi:[1,0]
	v_pk_mul_f32 v[34:35], v[34:35], s[10:11] op_sel_hi:[1,0]
	s_waitcnt vmcnt(5)
	v_pk_mul_f32 v[36:37], v[36:37], s[10:11] op_sel_hi:[1,0]
	v_pk_mul_f32 v[38:39], v[38:39], s[10:11] op_sel_hi:[1,0]
	s_waitcnt vmcnt(4)
	v_pk_mul_f32 v[40:41], v[40:41], s[10:11] op_sel_hi:[1,0]
	v_pk_mul_f32 v[42:43], v[42:43], s[10:11] op_sel_hi:[1,0]
	.p2align	6

; #define LAS __attribute__((address_space(3)))
; template <int MODE> __device__ __forceinline__ void conv_mat(const float* W, const float* nw, int K, int N, bf16* WT, LAS float* scr, int gw, int NGW, int lane) {
;     const int nblk = N / 32, nitems = (K / 64) * nblk;
;     for (int it = gw; it < nitems; it += NGW) { const int kb = it / nblk, nb = it % nblk, n0 = 32 * nb; int d = n0;
;         if (MODE == 1) { d = (n0 < DFF) ? 256 * (n0 / 128) + (n0 % 128) : 256 * ((n0 - DFF) / 128) + 128 + ((n0 - DFF) % 128); }
;         tr_item(W, nw, K, N, WT, 64 * kb, n0, d, scr, lane); }
; __global__ void __launch_bounds__(512, 2) fwd_megakernel(Args a) {
;     ...
;     conv_mat<1>(a.in[I_F2I], a.in[I_F2N], DM, 2 * DFF, WFI, scr, gw, NGW, lane);
.LBB0_1761:
	s_or_b64 exec, exec, s[4:5]
	v_readlane_b32 s0, v250, 10
	v_readlane_b32 s1, v250, 11
	s_and_b64 vcc, exec, s[0:1]
	s_waitcnt lgkmcnt(0)
	s_barrier
	s_cbranch_vccnz .LBB0_1776
	v_readlane_b32 s4, v250, 4
	v_lshlrev_b32_e32 v0, 4, v225
	v_mov_b32_e32 v1, 0
	v_readlane_b32 s3, v250, 3
	s_cmp_lg_u64 s[84:85], 0
	v_readlane_b32 s5, v250, 5
	v_lshl_add_u64 v[32:33], s[86:87], 0, v[0:1]
	v_add_u32_e32 v2, s3, v0
	s_cselect_b64 s[0:1], -1, 0
	v_mul_u32_u24_e32 v4, 0x420, v225
	v_lshl_add_u64 v[34:35], s[4:5], 0, v[0:1]
	v_lshlrev_b32_e32 v0, 2, v224
	v_mul_u32_u24_e32 v3, 0x84, v224
	v_add3_u32 v43, s3, v4, v0
	s_lshl_b32 s4, s34, 6
	v_cndmask_b32_e64 v0, 0, 1, s[0:1]
	v_or_b32_e32 v39, 8, v224
	v_or_b32_e32 v41, 16, v224
	v_or_b32_e32 v42, 24, v224
	s_lshl_b32 s3, s34, 5
	s_lshl_b32 s12, s64, 5
	s_add_i32 s13, s4, 0x7fffd400
	s_lshl_b32 s14, s64, 6
	s_mov_b32 s15, 0xb000
	v_cmp_ne_u32_e64 s[4:5], 1, v0
	v_add_u32_e32 v44, v2, v3
	s_mov_b32 s16, s34
	s_branch .LBB0_1764
	.p2align	6

; #define LAS __attribute__((address_space(3)))
; template <int MODE> __device__ __forceinline__ void conv_mat(const float* W, const float* nw, int K, int N, bf16* WT, LAS float* scr, int gw, int NGW, int lane) {
;     const int nblk = N / 32, nitems = (K / 64) * nblk;
;     for (int it = gw; it < nitems; it += NGW) { const int kb = it / nblk, nb = it % nblk, n0 = 32 * nb; int d = n0;
;         if (MODE == 1) { d = (n0 < DFF) ? 256 * (n0 / 128) + (n0 % 128) : 256 * ((n0 - DFF) / 128) + 128 + ((n0 - DFF) % 128); }
;         tr_item(W, nw, K, N, WT, 64 * kb, n0, d, scr, lane); }
; __global__ void __launch_bounds__(512, 2) fwd_megakernel(Args a) {
;     ...
;     conv_mat<0>(a.in[I_F2O], nullptr, DFF, DM, WFO, scr, gw, NGW, lane);
.LBB0_1776:
	v_readlane_b32 s0, v250, 6
	v_readlane_b32 s1, v250, 7
	v_readlane_b32 s72, v250, 32
	s_andn2_b64 vcc, exec, s[0:1]
	v_readlane_b32 s73, v250, 33
	s_cbranch_vccnz .LBB0_1779
	v_lshlrev_b32_e32 v2, 4, v225
	v_readlane_b32 s0, v250, 3
	v_mul_u32_u24_e32 v7, 0x84, v224
	v_mul_u32_u24_e32 v4, 0x420, v225
	v_add_u32_e32 v6, s0, v2
	v_lshlrev_b32_e32 v5, 2, v224
	v_readlane_b32 s1, v250, 8
	v_mov_b32_e32 v3, 0
	v_add3_u32 v4, s0, v4, v5
	s_movk_i32 s0, 0x1600
	v_mov_b32_e32 v5, s1
	v_add_u32_e32 v6, v6, v7
	v_lshl_add_u64 v[0:1], s[88:89], 0, v[2:3]
	v_lshl_add_u64 v[2:3], s[68:69], 0, v[2:3]
	v_mad_u32_u24 v5, v224, s0, v5
	s_lshl_b32 s3, s34, 5
	s_lshl_b32 s4, s64, 5
	v_add_u32_e32 v7, 0x420, v6
	v_add_u32_e32 v8, 0x428, v6
	v_add_u32_e32 v9, 0x840, v6
	v_add_u32_e32 v10, 0x848, v6
	v_add_u32_e32 v11, 0xc60, v6
	v_add_u32_e32 v12, 0xc68, v6
	v_add_u32_e32 v13, 0x1080, v6
	v_add_u32_e32 v14, 0x1088, v6
	v_add_u32_e32 v15, 0x14a0, v6
	v_add_u32_e32 v16, 0x14a8, v6
	v_add_u32_e32 v17, 0x18c0, v6
	v_add_u32_e32 v18, 0x18c8, v6
	v_add_u32_e32 v19, 0x1ce0, v6
	v_add_u32_e32 v20, 0x1ce8, v6
	s_mov_b32 s5, s34
	v_readlane_b32 s11, v250, 9
	.p2align	6
